# NSA selected-block and MoBA past-block steps: exp / cvt / row-sum VALU interleaved with the P.V MFMAs (window-step schedule transplanted, block mask ANDed into P)
# speedup vs baseline: 1.0004x; 1.0004x over previous
.LBB0_109:
	s_and_b64 vcc, exec, s[40:41]
	s_cbranch_vccnz .Lsel_masked
	v_exp_f32_e32 v157, v50
	v_exp_f32_e32 v159, v51
	v_exp_f32_e32 v161, v52
	v_exp_f32_e32 v177, v53
	ds_read_b128 v[50:53], v146 offset:61440
	v_exp_f32_e32 v179, v54
	v_exp_f32_e32 v233, v55
	v_exp_f32_e32 v235, v56
	v_exp_f32_e32 v237, v57
	v_exp_f32_e32 v156, v66
	v_exp_f32_e32 v158, v67
	v_exp_f32_e32 v160, v68
	v_exp_f32_e32 v176, v69
	v_cvt_pk_bf16_f32 v66, v157, v159
	v_cvt_pk_bf16_f32 v67, v161, v177
	v_cvt_pk_bf16_f32 v68, v179, v233
	v_cvt_pk_bf16_f32 v69, v235, v237
	ds_read_b128 v[54:57], v147 offset:61440
	v_exp_f32_e32 v178, v70
	s_waitcnt lgkmcnt(5)
	v_mfma_f32_32x32x16_bf16 v[2:17], v[114:117], v[66:69], v[2:17]
	v_exp_f32_e32 v239, v58
	v_exp_f32_e32 v59, v59
	v_exp_f32_e32 v241, v60
	v_exp_f32_e32 v61, v61
	v_exp_f32_e32 v243, v62
	v_exp_f32_e32 v63, v63
	v_exp_f32_e32 v115, v64
	s_waitcnt lgkmcnt(1)
	v_mfma_f32_32x32x16_bf16 v[18:33], v[50:53], v[66:69], v[18:33]
	v_exp_f32_e32 v65, v65
	v_pk_add_f32 v[66:67], v[156:157], 0 op_sel_hi:[1,0]
	v_exp_f32_e32 v232, v71
	v_pk_add_f32 v[66:67], v[158:159], v[66:67]
	v_exp_f32_e32 v234, v72
	v_pk_add_f32 v[66:67], v[160:161], v[66:67]
	v_exp_f32_e32 v236, v73
	v_pk_add_f32 v[66:67], v[176:177], v[66:67]
	v_cvt_pk_bf16_f32 v70, v239, v59
	v_cvt_pk_bf16_f32 v71, v241, v61
	v_cvt_pk_bf16_f32 v72, v243, v63
	v_cvt_pk_bf16_f32 v73, v115, v65
	v_pk_add_f32 v[50:51], v[178:179], v[66:67]
	ds_read_b128 v[66:69], v144 offset:61440
	v_mfma_f32_32x32x16_bf16 v[2:17], v[110:113], v[70:73], v[2:17]
	v_exp_f32_e32 v238, v74
	v_exp_f32_e32 v58, v75
	v_exp_f32_e32 v240, v76
	v_exp_f32_e32 v60, v77
	v_cvt_pk_bf16_f32 v74, v156, v158
	v_cvt_pk_bf16_f32 v75, v160, v176
	v_cvt_pk_bf16_f32 v76, v178, v232
	s_waitcnt lgkmcnt(1)
	v_mfma_f32_32x32x16_bf16 v[18:33], v[54:57], v[70:73], v[18:33]
	v_add_f32_e64 v70, v232, v50
	v_add_f32_e64 v71, v233, v51
	v_cvt_pk_bf16_f32 v77, v234, v236
	v_add_f32_e64 v70, v234, v70
	v_add_f32_e64 v71, v235, v71
	v_exp_f32_e32 v242, v78
	v_pk_add_f32 v[70:71], v[236:237], v[70:71]
	v_exp_f32_e32 v62, v79
	v_pk_add_f32 v[70:71], v[238:239], v[70:71]
	v_mfma_f32_32x32x16_bf16 v[2:17], v[118:121], v[74:77], v[2:17]
	v_add_f32_e64 v70, v58, v70
	v_add_f32_e64 v71, v59, v71
	v_exp_f32_e32 v114, v80
	v_pk_add_f32 v[50:51], v[240:241], v[70:71]
	ds_read_b128 v[70:73], v145 offset:61440
	v_exp_f32_e32 v64, v81
	v_cvt_pk_bf16_f32 v78, v238, v58
	v_cvt_pk_bf16_f32 v79, v240, v60
	s_waitcnt lgkmcnt(1)
	v_mfma_f32_32x32x16_bf16 v[18:33], v[66:69], v[74:77], v[18:33]
	v_cvt_pk_bf16_f32 v80, v242, v62
	v_cvt_pk_bf16_f32 v81, v114, v64
	v_add_f32_e64 v66, v60, v50
	v_add_f32_e64 v67, v61, v51
	v_cmp_lt_f32_e32 vcc, s24, v148
	s_or_b64 s[0:1], s[0:1], vcc
	v_pk_add_f32 v[66:67], v[242:243], v[66:67]
	v_pk_add_f32 v[66:67], v[62:63], v[66:67]
	v_mfma_f32_32x32x16_bf16 v[2:17], v[122:125], v[78:81], v[2:17]
	v_add_f32_e64 v66, v114, v66
	v_add_f32_e64 v67, v115, v67
	v_add_f32_e64 v66, v64, v66
	v_add_f32_e64 v67, v65, v67
	v_add_f32_e32 v66, v66, v67
	s_waitcnt lgkmcnt(0)
	v_mfma_f32_32x32x16_bf16 v[18:33], v[70:73], v[78:81], v[18:33]
	v_add_f32_e32 v127, v127, v66
	s_branch .LBB0_105
.Lsel_masked:
	v_cndmask_b32_e64 v203, 0, -1, s[38:39]
	v_exp_f32_e32 v157, v50
	v_exp_f32_e32 v159, v51
	v_exp_f32_e32 v161, v52
	v_exp_f32_e32 v177, v53
	ds_read_b128 v[50:53], v146 offset:61440
	v_exp_f32_e32 v179, v54
	v_exp_f32_e32 v233, v55
	v_exp_f32_e32 v235, v56
	v_exp_f32_e32 v237, v57
	v_exp_f32_e32 v156, v66
	v_exp_f32_e32 v158, v67
	v_exp_f32_e32 v160, v68
	v_exp_f32_e32 v176, v69
	v_cvt_pk_bf16_f32 v66, v157, v159
	v_and_b32_e32 v66, v66, v203
	v_cvt_pk_bf16_f32 v67, v161, v177
	v_and_b32_e32 v67, v67, v203
	v_cvt_pk_bf16_f32 v68, v179, v233
	v_and_b32_e32 v68, v68, v203
	v_cvt_pk_bf16_f32 v69, v235, v237
	v_and_b32_e32 v69, v69, v203
	ds_read_b128 v[54:57], v147 offset:61440
	v_exp_f32_e32 v178, v70
	s_waitcnt lgkmcnt(5)
	v_mfma_f32_32x32x16_bf16 v[2:17], v[114:117], v[66:69], v[2:17]
	v_exp_f32_e32 v239, v58
	v_exp_f32_e32 v59, v59
	v_exp_f32_e32 v241, v60
	v_exp_f32_e32 v61, v61
	v_exp_f32_e32 v243, v62
	v_exp_f32_e32 v63, v63
	v_exp_f32_e32 v115, v64
	s_waitcnt lgkmcnt(1)
	v_mfma_f32_32x32x16_bf16 v[18:33], v[50:53], v[66:69], v[18:33]
	v_exp_f32_e32 v65, v65
	v_pk_add_f32 v[66:67], v[156:157], 0 op_sel_hi:[1,0]
	v_exp_f32_e32 v232, v71
	v_pk_add_f32 v[66:67], v[158:159], v[66:67]
	v_exp_f32_e32 v234, v72
	v_pk_add_f32 v[66:67], v[160:161], v[66:67]
	v_exp_f32_e32 v236, v73
	v_pk_add_f32 v[66:67], v[176:177], v[66:67]
	v_cvt_pk_bf16_f32 v70, v239, v59
	v_and_b32_e32 v70, v70, v203
	v_cvt_pk_bf16_f32 v71, v241, v61
	v_and_b32_e32 v71, v71, v203
	v_cvt_pk_bf16_f32 v72, v243, v63
	v_and_b32_e32 v72, v72, v203
	v_cvt_pk_bf16_f32 v73, v115, v65
	v_and_b32_e32 v73, v73, v203
	v_pk_add_f32 v[50:51], v[178:179], v[66:67]
	ds_read_b128 v[66:69], v144 offset:61440
	v_mfma_f32_32x32x16_bf16 v[2:17], v[110:113], v[70:73], v[2:17]
	v_exp_f32_e32 v238, v74
	v_exp_f32_e32 v58, v75
	v_exp_f32_e32 v240, v76
	v_exp_f32_e32 v60, v77
	v_cvt_pk_bf16_f32 v74, v156, v158
	v_and_b32_e32 v74, v74, v203
	v_cvt_pk_bf16_f32 v75, v160, v176
	v_and_b32_e32 v75, v75, v203
	v_cvt_pk_bf16_f32 v76, v178, v232
	v_and_b32_e32 v76, v76, v203
	s_waitcnt lgkmcnt(1)
	v_mfma_f32_32x32x16_bf16 v[18:33], v[54:57], v[70:73], v[18:33]
	v_add_f32_e64 v70, v232, v50
	v_add_f32_e64 v71, v233, v51
	v_cvt_pk_bf16_f32 v77, v234, v236
	v_and_b32_e32 v77, v77, v203
	v_add_f32_e64 v70, v234, v70
	v_add_f32_e64 v71, v235, v71
	v_exp_f32_e32 v242, v78
	v_pk_add_f32 v[70:71], v[236:237], v[70:71]
	v_exp_f32_e32 v62, v79
	v_pk_add_f32 v[70:71], v[238:239], v[70:71]
	v_mfma_f32_32x32x16_bf16 v[2:17], v[118:121], v[74:77], v[2:17]
	v_add_f32_e64 v70, v58, v70
	v_add_f32_e64 v71, v59, v71
	v_exp_f32_e32 v114, v80
	v_pk_add_f32 v[50:51], v[240:241], v[70:71]
	ds_read_b128 v[70:73], v145 offset:61440
	v_exp_f32_e32 v64, v81
	v_cvt_pk_bf16_f32 v78, v238, v58
	v_and_b32_e32 v78, v78, v203
	v_cvt_pk_bf16_f32 v79, v240, v60
	v_and_b32_e32 v79, v79, v203
	s_waitcnt lgkmcnt(1)
	v_mfma_f32_32x32x16_bf16 v[18:33], v[66:69], v[74:77], v[18:33]
	v_cvt_pk_bf16_f32 v80, v242, v62
	v_and_b32_e32 v80, v80, v203
	v_cvt_pk_bf16_f32 v81, v114, v64
	v_and_b32_e32 v81, v81, v203
	v_add_f32_e64 v66, v60, v50
	v_add_f32_e64 v67, v61, v51
	v_cmp_lt_f32_e32 vcc, s24, v148
	s_or_b64 s[0:1], s[0:1], vcc
	v_pk_add_f32 v[66:67], v[242:243], v[66:67]
	v_pk_add_f32 v[66:67], v[62:63], v[66:67]
	v_mfma_f32_32x32x16_bf16 v[2:17], v[122:125], v[78:81], v[2:17]
	v_add_f32_e64 v66, v114, v66
	v_add_f32_e64 v67, v115, v67
	v_add_f32_e64 v66, v64, v66
	v_add_f32_e64 v67, v65, v67
	v_add_f32_e32 v66, v66, v67
	s_waitcnt lgkmcnt(0)
	v_mfma_f32_32x32x16_bf16 v[18:33], v[70:73], v[78:81], v[18:33]
	v_and_b32_e32 v66, v66, v203
	v_add_f32_e32 v127, v127, v66
	s_branch .LBB0_105

.LBB0_365:
	s_and_b64 vcc, exec, s[38:39]
	s_cbranch_vccnz .Lmoba_masked
	v_exp_f32_e32 v233, v64
	v_exp_f32_e32 v235, v65
	v_exp_f32_e32 v237, v66
	v_exp_f32_e32 v209, v67
	ds_read_b128 v[64:67], v145 offset:61440
	v_exp_f32_e32 v211, v68
	v_exp_f32_e32 v213, v69
	v_exp_f32_e32 v215, v70
	v_exp_f32_e32 v217, v71
	v_exp_f32_e32 v232, v80
	v_exp_f32_e32 v234, v81
	v_exp_f32_e32 v236, v82
	v_exp_f32_e32 v208, v83
	v_cvt_pk_bf16_f32 v80, v233, v235
	v_cvt_pk_bf16_f32 v81, v237, v209
	v_cvt_pk_bf16_f32 v82, v211, v213
	v_cvt_pk_bf16_f32 v83, v215, v217
	ds_read_b128 v[68:71], v146 offset:61440
	v_exp_f32_e32 v210, v84
	s_waitcnt lgkmcnt(5)
	v_mfma_f32_32x32x16_bf16 v[32:47], v[6:9], v[80:83], v[32:47]
	v_exp_f32_e32 v219, v72
	v_exp_f32_e32 v73, v73
	v_exp_f32_e32 v221, v74
	v_exp_f32_e32 v75, v75
	v_exp_f32_e32 v239, v76
	v_exp_f32_e32 v77, v77
	v_exp_f32_e32 v7, v78
	s_waitcnt lgkmcnt(1)
	v_mfma_f32_32x32x16_bf16 v[16:31], v[64:67], v[80:83], v[16:31]
	v_exp_f32_e32 v79, v79
	v_pk_add_f32 v[80:81], v[232:233], 0 op_sel_hi:[1,0]
	v_exp_f32_e32 v212, v85
	v_pk_add_f32 v[80:81], v[234:235], v[80:81]
	v_exp_f32_e32 v214, v86
	v_pk_add_f32 v[80:81], v[236:237], v[80:81]
	v_exp_f32_e32 v216, v87
	v_pk_add_f32 v[80:81], v[208:209], v[80:81]
	v_cvt_pk_bf16_f32 v84, v219, v73
	v_cvt_pk_bf16_f32 v85, v221, v75
	v_cvt_pk_bf16_f32 v86, v239, v77
	v_cvt_pk_bf16_f32 v87, v7, v79
	v_pk_add_f32 v[64:65], v[210:211], v[80:81]
	ds_read_b128 v[80:83], v14 offset:61440
	v_mfma_f32_32x32x16_bf16 v[32:47], v[2:5], v[84:87], v[32:47]
	v_exp_f32_e32 v218, v88
	v_exp_f32_e32 v72, v89
	v_exp_f32_e32 v220, v90
	v_exp_f32_e32 v74, v91
	v_cvt_pk_bf16_f32 v88, v232, v234
	v_cvt_pk_bf16_f32 v89, v236, v208
	v_cvt_pk_bf16_f32 v90, v210, v212
	s_waitcnt lgkmcnt(1)
	v_mfma_f32_32x32x16_bf16 v[16:31], v[68:71], v[84:87], v[16:31]
	v_add_f32_e64 v84, v212, v64
	v_add_f32_e64 v85, v213, v65
	v_cvt_pk_bf16_f32 v91, v214, v216
	v_add_f32_e64 v84, v214, v84
	v_add_f32_e64 v85, v215, v85
	v_exp_f32_e32 v238, v92
	v_pk_add_f32 v[84:85], v[216:217], v[84:85]
	v_exp_f32_e32 v76, v93
	v_pk_add_f32 v[84:85], v[218:219], v[84:85]
	v_mfma_f32_32x32x16_bf16 v[32:47], v[10:13], v[88:91], v[32:47]
	v_add_f32_e64 v84, v72, v84
	v_add_f32_e64 v85, v73, v85
	v_exp_f32_e32 v6, v94
	v_pk_add_f32 v[64:65], v[220:221], v[84:85]
	ds_read_b128 v[84:87], v15 offset:61440
	v_exp_f32_e32 v78, v95
	v_cvt_pk_bf16_f32 v92, v218, v72
	v_cvt_pk_bf16_f32 v93, v220, v74
	s_waitcnt lgkmcnt(1)
	v_mfma_f32_32x32x16_bf16 v[16:31], v[80:83], v[88:91], v[16:31]
	v_cvt_pk_bf16_f32 v94, v238, v76
	v_cvt_pk_bf16_f32 v95, v6, v78
	v_add_f32_e64 v80, v74, v64
	v_add_f32_e64 v81, v75, v65
	v_cmp_lt_f32_e32 vcc, s24, v147
	s_or_b64 s[30:31], s[30:31], vcc
	v_pk_add_f32 v[80:81], v[238:239], v[80:81]
	v_pk_add_f32 v[80:81], v[76:77], v[80:81]
	v_mfma_f32_32x32x16_bf16 v[32:47], v[122:125], v[92:95], v[32:47]
	v_add_f32_e64 v80, v6, v80
	v_add_f32_e64 v81, v7, v81
	v_add_f32_e64 v80, v78, v80
	v_add_f32_e64 v81, v79, v81
	v_add_f32_e32 v80, v80, v81
	s_waitcnt lgkmcnt(0)
	v_mfma_f32_32x32x16_bf16 v[16:31], v[84:87], v[92:95], v[16:31]
	v_add_f32_e32 v0, v0, v80
	s_branch .LBB0_361
.Lmoba_masked:
	v_cndmask_b32_e64 v203, 0, -1, s[36:37]
	v_exp_f32_e32 v233, v64
	v_exp_f32_e32 v235, v65
	v_exp_f32_e32 v237, v66
	v_exp_f32_e32 v209, v67
	ds_read_b128 v[64:67], v145 offset:61440
	v_exp_f32_e32 v211, v68
	v_exp_f32_e32 v213, v69
	v_exp_f32_e32 v215, v70
	v_exp_f32_e32 v217, v71
	v_exp_f32_e32 v232, v80
	v_exp_f32_e32 v234, v81
	v_exp_f32_e32 v236, v82
	v_exp_f32_e32 v208, v83
	v_cvt_pk_bf16_f32 v80, v233, v235
	v_and_b32_e32 v80, v80, v203
	v_cvt_pk_bf16_f32 v81, v237, v209
	v_and_b32_e32 v81, v81, v203
	v_cvt_pk_bf16_f32 v82, v211, v213
	v_and_b32_e32 v82, v82, v203
	v_cvt_pk_bf16_f32 v83, v215, v217
	v_and_b32_e32 v83, v83, v203
	ds_read_b128 v[68:71], v146 offset:61440
	v_exp_f32_e32 v210, v84
	s_waitcnt lgkmcnt(5)
	v_mfma_f32_32x32x16_bf16 v[32:47], v[6:9], v[80:83], v[32:47]
	v_exp_f32_e32 v219, v72
	v_exp_f32_e32 v73, v73
	v_exp_f32_e32 v221, v74
	v_exp_f32_e32 v75, v75
	v_exp_f32_e32 v239, v76
	v_exp_f32_e32 v77, v77
	v_exp_f32_e32 v7, v78
	s_waitcnt lgkmcnt(1)
	v_mfma_f32_32x32x16_bf16 v[16:31], v[64:67], v[80:83], v[16:31]
	v_exp_f32_e32 v79, v79
	v_pk_add_f32 v[80:81], v[232:233], 0 op_sel_hi:[1,0]
	v_exp_f32_e32 v212, v85
	v_pk_add_f32 v[80:81], v[234:235], v[80:81]
	v_exp_f32_e32 v214, v86
	v_pk_add_f32 v[80:81], v[236:237], v[80:81]
	v_exp_f32_e32 v216, v87
	v_pk_add_f32 v[80:81], v[208:209], v[80:81]
	v_cvt_pk_bf16_f32 v84, v219, v73
	v_and_b32_e32 v84, v84, v203
	v_cvt_pk_bf16_f32 v85, v221, v75
	v_and_b32_e32 v85, v85, v203
	v_cvt_pk_bf16_f32 v86, v239, v77
	v_and_b32_e32 v86, v86, v203
	v_cvt_pk_bf16_f32 v87, v7, v79
	v_and_b32_e32 v87, v87, v203
	v_pk_add_f32 v[64:65], v[210:211], v[80:81]
	ds_read_b128 v[80:83], v14 offset:61440
	v_mfma_f32_32x32x16_bf16 v[32:47], v[2:5], v[84:87], v[32:47]
	v_exp_f32_e32 v218, v88
	v_exp_f32_e32 v72, v89
	v_exp_f32_e32 v220, v90
	v_exp_f32_e32 v74, v91
	v_cvt_pk_bf16_f32 v88, v232, v234
	v_and_b32_e32 v88, v88, v203
	v_cvt_pk_bf16_f32 v89, v236, v208
	v_and_b32_e32 v89, v89, v203
	v_cvt_pk_bf16_f32 v90, v210, v212
	v_and_b32_e32 v90, v90, v203
	s_waitcnt lgkmcnt(1)
	v_mfma_f32_32x32x16_bf16 v[16:31], v[68:71], v[84:87], v[16:31]
	v_add_f32_e64 v84, v212, v64
	v_add_f32_e64 v85, v213, v65
	v_cvt_pk_bf16_f32 v91, v214, v216
	v_and_b32_e32 v91, v91, v203
	v_add_f32_e64 v84, v214, v84
	v_add_f32_e64 v85, v215, v85
	v_exp_f32_e32 v238, v92
	v_pk_add_f32 v[84:85], v[216:217], v[84:85]
	v_exp_f32_e32 v76, v93
	v_pk_add_f32 v[84:85], v[218:219], v[84:85]
	v_mfma_f32_32x32x16_bf16 v[32:47], v[10:13], v[88:91], v[32:47]
	v_add_f32_e64 v84, v72, v84
	v_add_f32_e64 v85, v73, v85
	v_exp_f32_e32 v6, v94
	v_pk_add_f32 v[64:65], v[220:221], v[84:85]
	ds_read_b128 v[84:87], v15 offset:61440
	v_exp_f32_e32 v78, v95
	v_cvt_pk_bf16_f32 v92, v218, v72
	v_and_b32_e32 v92, v92, v203
	v_cvt_pk_bf16_f32 v93, v220, v74
	v_and_b32_e32 v93, v93, v203
	s_waitcnt lgkmcnt(1)
	v_mfma_f32_32x32x16_bf16 v[16:31], v[80:83], v[88:91], v[16:31]
	v_cvt_pk_bf16_f32 v94, v238, v76
	v_and_b32_e32 v94, v94, v203
	v_cvt_pk_bf16_f32 v95, v6, v78
	v_and_b32_e32 v95, v95, v203
	v_add_f32_e64 v80, v74, v64
	v_add_f32_e64 v81, v75, v65
	v_cmp_lt_f32_e32 vcc, s24, v147
	s_or_b64 s[30:31], s[30:31], vcc
	v_pk_add_f32 v[80:81], v[238:239], v[80:81]
	v_pk_add_f32 v[80:81], v[76:77], v[80:81]
	v_mfma_f32_32x32x16_bf16 v[32:47], v[122:125], v[92:95], v[32:47]
	v_add_f32_e64 v80, v6, v80
	v_add_f32_e64 v81, v7, v81
	v_add_f32_e64 v80, v78, v80
	v_add_f32_e64 v81, v79, v81
	v_add_f32_e32 v80, v80, v81
	s_waitcnt lgkmcnt(0)
	v_mfma_f32_32x32x16_bf16 v[16:31], v[84:87], v[92:95], v[16:31]
	v_and_b32_e32 v80, v80, v203
	v_add_f32_e32 v0, v0, v80
	s_branch .LBB0_361
